# ctx units on RG workgroups; SSD workgroups run their scan unit first; combine slices taken by RG workgroups
# baseline (speedup 1.0000x reference)
.LBB0_687:
	v_readlane_b32 s0, v254, 32
	s_cmp_eq_u32 s28, s0
	s_mov_b64 s[4:5], -1
	s_cbranch_scc1 .LBB0_686
	s_add_i32 s28, s28, 1
	v_readlane_b32 s0, v254, 31
	s_cmp_lt_i32 s28, s0
	s_mul_i32 s16, s28, s85
	s_cselect_b32 s31, s16, 0
	s_cmpk_lt_u32 s79, 0x80
	s_cbranch_scc1 .Lunit_order_done
	s_sub_i32 s31, s16, s85
.Lunit_order_done:
	s_add_i32 s22, s31, s79
	s_cmpk_gt_i32 s22, 0xff
	s_cselect_b64 s[4:5], -1, 0
	s_and_b64 vcc, exec, s[4:5]
	s_cbranch_vccnz .LBB0_691
	s_and_saveexec_b64 s[6:7], s[34:35]
	s_cbranch_execz .LBB0_739
	s_mov_b32 s0, 0x400001
	s_mov_b64 s[8:9], 0
	s_branch .LBB0_732

.LBB0_894:
	v_readlane_b32 s0, v254, 8
	v_readlane_b32 s1, v254, 9
	s_mov_b32 s91, s79
	s_andn2_b64 vcc, exec, s[0:1]
	s_cbranch_vccnz .LBB0_947
	v_readlane_b32 s0, v255, 16
	s_mov_b32 s2, s0
	s_lshl_b32 s0, s0, 2
	s_lshl_b32 s36, s2, 8
	s_cmpk_lt_i32 s61, 0x80
	v_readlane_b32 s1, v255, 17
	s_cselect_b64 s[12:13], -1, 0
	s_add_u32 s14, s20, 0x6600000
	s_addc_u32 s15, s21, 0
	s_add_i32 s1, s61, 0x8000
	s_cmp_lt_i32 s61, 16
	s_cselect_b64 s[16:17], -1, 0
	s_cmp_lt_i32 s61, 8
	s_cselect_b64 s[30:31], -1, 0
	s_cmp_lt_i32 s61, 0
	s_cselect_b64 s[38:39], -1, 0
	s_add_i32 s22, s61, 32
	s_add_i32 s23, s61, 48
	s_add_u32 s24, s20, 0x9c00400
	s_addc_u32 s25, s21, 0
	s_add_u32 s26, s20, 0x16200200
	s_addc_u32 s27, s21, 0
	s_add_i32 s28, s61, 24
	s_lshl_b64 s[40:41], s[36:37], 2
	s_mov_b32 s33, s91
	s_mov_b32 s29, s91
	s_cmpk_lt_u32 s79, 0x80
	s_cbranch_scc0 .LBB0_947
	s_movk_i32 s100, 0x80
	s_cmp_eq_u64 s[82:83], 0
	s_cbranch_scc1 .Lcmb_go
	s_movk_i32 s100, 0x100
	s_cmpk_lt_u32 s79, 0x40
	s_cbranch_scc1 .Lcmb_go
	s_movk_i32 s100, 0x40
.Lcmb_go:
	s_branch .LBB0_898
.LBB0_896:
	s_and_b64 vcc, exec, s[2:3]
	s_cbranch_vccz .LBB0_946
.LBB0_897:
	s_add_i32 s33, s33, s100
	s_add_i32 s29, s29, s100
	s_cmpk_gt_i32 s33, 0xff
	s_cbranch_scc1 .LBB0_947

	.amdhsa_kernel _Z10hybrid_fwd4Args
		.amdhsa_group_segment_fixed_size 0
		.amdhsa_private_segment_fixed_size 0
		.amdhsa_kernarg_size 504
		.amdhsa_user_sgpr_count 2
		.amdhsa_user_sgpr_dispatch_ptr 0
		.amdhsa_user_sgpr_queue_ptr 0
		.amdhsa_user_sgpr_kernarg_segment_ptr 1
		.amdhsa_user_sgpr_dispatch_id 0
		.amdhsa_user_sgpr_kernarg_preload_length 0
		.amdhsa_user_sgpr_kernarg_preload_offset 0
		.amdhsa_user_sgpr_private_segment_size 0
		.amdhsa_uses_dynamic_stack 0
		.amdhsa_enable_private_segment 0
		.amdhsa_system_sgpr_workgroup_id_x 1
		.amdhsa_system_sgpr_workgroup_id_y 0
		.amdhsa_system_sgpr_workgroup_id_z 0
		.amdhsa_system_sgpr_workgroup_info 0
		.amdhsa_system_vgpr_workitem_id 2
		.amdhsa_next_free_vgpr 256
		.amdhsa_next_free_sgpr 102
		.amdhsa_accum_offset 256
		.amdhsa_reserve_vcc 1
		.amdhsa_float_round_mode_32 0
		.amdhsa_float_round_mode_16_64 0
		.amdhsa_float_denorm_mode_32 3
		.amdhsa_float_denorm_mode_16_64 3
		.amdhsa_dx10_clamp 1
		.amdhsa_ieee_mode 1
		.amdhsa_fp16_overflow 0
		.amdhsa_tg_split 0
		.amdhsa_exception_fp_ieee_invalid_op 0
		.amdhsa_exception_fp_denorm_src 0
		.amdhsa_exception_fp_ieee_div_zero 0
		.amdhsa_exception_fp_ieee_overflow 0
		.amdhsa_exception_fp_ieee_underflow 0
		.amdhsa_exception_fp_ieee_inexact 0
		.amdhsa_exception_int_div_zero 0
	.end_amdhsa_kernel

amdhsa.kernels:
  - .agpr_count:     0
    .args:
      - .offset:         0
        .size:           248
        .value_kind:     by_value
      - .offset:         248
        .size:           4
        .value_kind:     hidden_block_count_x
      - .offset:         252
        .size:           4
        .value_kind:     hidden_block_count_y
      - .offset:         256
        .size:           4
        .value_kind:     hidden_block_count_z
      - .offset:         260
        .size:           2
        .value_kind:     hidden_group_size_x
      - .offset:         262
        .size:           2
        .value_kind:     hidden_group_size_y
      - .offset:         264
        .size:           2
        .value_kind:     hidden_group_size_z
      - .offset:         266
        .size:           2
        .value_kind:     hidden_remainder_x
      - .offset:         268
        .size:           2
        .value_kind:     hidden_remainder_y
      - .offset:         270
        .size:           2
        .value_kind:     hidden_remainder_z
      - .offset:         288
        .size:           8
        .value_kind:     hidden_global_offset_x
      - .offset:         296
        .size:           8
        .value_kind:     hidden_global_offset_y
      - .offset:         304
        .size:           8
        .value_kind:     hidden_global_offset_z
      - .offset:         312
        .size:           2
        .value_kind:     hidden_grid_dims
      - .offset:         336
        .size:           8
        .value_kind:     hidden_multigrid_sync_arg
      - .offset:         368
        .size:           4
        .value_kind:     hidden_dynamic_lds_size
    .group_segment_fixed_size: 0
    .kernarg_segment_align: 8
    .kernarg_segment_size: 504
    .language:       OpenCL C
    .language_version:
      - 2
      - 0
    .max_flat_workgroup_size: 512
    .name:           _Z10hybrid_fwd4Args
    .private_segment_fixed_size: 0
    .sgpr_count:     108
    .sgpr_spill_count: 124
    .symbol:         _Z10hybrid_fwd4Args.kd
    .uniform_work_group_size: 1
    .uses_dynamic_stack: false
    .vgpr_count:     256
    .vgpr_spill_count: 0
    .wavefront_size: 64
